# v33 + P0a modulation GEMV k-loop: three loads of the second group issued before the first full wait
# speedup vs baseline: 1.0013x; 1.0013x over previous
; __device__ __forceinline__ void phase_p0a(const Args& a, LAS unsigned char* lds) {
;     ...
;             for (int k0 = 0; k0 < 128; k0 += 32) {
;                 f32x2 wv[32];
; #pragma unroll
;                 for (int kk = 0; kk < 32; ++kk) wv[kk] = *(const f32x2*)(wp + (size_t)(k0 + kk) * NMODC);
; #pragma unroll
;                 for (int kk = 0; kk < 32; ++kk) {
; #pragma unroll
;                     for (int bb = 0; bb < 5; ++bb) { const float sv = sil[bb * DM + wave * 128 + k0 + kk]; acc[bb][0] += sv * wv[kk][0]; acc[bb][1] += sv * wv[kk][1]; }
.LBB0_913:
	v_add_co_u32_e32 v2, vcc, 0x6000, v44
	s_add_i32 s5, s5, 32
	s_nop 0
	v_addc_co_u32_e32 v3, vcc, 0, v45, vcc
	v_add_co_u32_e32 v4, vcc, 0xc000, v44
	s_cmpk_gt_u32 s5, 0x5f
	s_nop 0
	v_addc_co_u32_e32 v5, vcc, 0, v45, vcc
	v_add_co_u32_e32 v6, vcc, 0x12000, v44
	global_load_dwordx2 v[70:71], v[2:3], off
	global_load_dwordx2 v[72:73], v[4:5], off
	v_addc_co_u32_e32 v7, vcc, 0, v45, vcc
	v_add_co_u32_e32 v2, vcc, 0x18000, v44
	s_nop 1
	v_addc_co_u32_e32 v3, vcc, 0, v45, vcc
	v_add_co_u32_e32 v62, vcc, s26, v44
	s_mov_b64 s[82:83], vcc
	v_add_co_u32_e32 v64, vcc, 0x24000, v44
	s_mov_b64 s[88:89], vcc
	v_add_co_u32_e32 v66, vcc, 0x2a000, v44
	s_mov_b64 s[84:85], vcc
	v_add_co_u32_e32 v68, vcc, 0x30000, v44
	s_mov_b64 s[86:87], vcc
	v_add_co_u32_e32 v48, vcc, 0x36000, v44
	s_mov_b64 s[74:75], vcc
	v_add_co_u32_e32 v50, vcc, 0x3c000, v44
	s_mov_b64 s[80:81], vcc
	v_add_co_u32_e32 v52, vcc, 0x42000, v44
	s_mov_b64 s[76:77], vcc
	v_add_co_u32_e32 v54, vcc, 0x48000, v44
	s_mov_b64 s[78:79], vcc
	v_add_co_u32_e32 v22, vcc, 0x4e000, v44
	s_mov_b64 s[66:67], vcc
	v_add_co_u32_e32 v24, vcc, 0x54000, v44
	s_mov_b64 s[0:1], vcc
	v_add_co_u32_e32 v34, vcc, 0x5a000, v44
	s_mov_b64 s[68:69], vcc
	v_add_co_u32_e32 v36, vcc, s33, v44
	s_mov_b64 s[70:71], vcc
	v_add_co_u32_e32 v4, vcc, 0x66000, v44
	global_load_dwordx2 v[74:75], v[6:7], off
	global_load_dwordx2 v[58:59], v[2:3], off
	s_mov_b64 s[58:59], vcc
	v_add_co_u32_e32 v6, vcc, s31, v44
	s_mov_b64 s[64:65], vcc
	v_add_co_u32_e32 v18, vcc, 0x72000, v44
	s_mov_b64 s[60:61], vcc
	v_add_co_u32_e32 v20, vcc, s2, v44
	s_mov_b64 s[62:63], vcc
	v_add_co_u32_e32 v26, vcc, 0x7e000, v44
	s_mov_b64 s[50:51], vcc
	v_add_co_u32_e32 v30, vcc, 0x84000, v44
	s_mov_b64 s[54:55], vcc
	v_add_co_u32_e32 v28, vcc, 0x8a000, v44
	s_mov_b64 s[52:53], vcc
	v_add_co_u32_e32 v32, vcc, s3, v44
	s_mov_b64 s[56:57], vcc
	v_add_co_u32_e32 v2, vcc, 0x96000, v44
	s_mov_b64 s[38:39], vcc
	v_add_co_u32_e32 v8, vcc, 0x9c000, v44
	s_mov_b64 s[48:49], vcc
	v_add_co_u32_e32 v10, vcc, 0xa2000, v44
	s_mov_b64 s[40:41], vcc
	v_add_co_u32_e32 v12, vcc, s30, v44
	s_mov_b64 s[42:43], vcc
	v_add_co_u32_e32 v14, vcc, 0xae000, v44
	s_mov_b64 s[44:45], vcc
	v_add_co_u32_e32 v16, vcc, 0xb4000, v44
	s_mov_b64 s[46:47], vcc
	v_add_co_u32_e32 v46, vcc, 0xba000, v44
	s_nop 1
	v_addc_co_u32_e32 v47, vcc, 0, v45, vcc
	global_load_dwordx2 v[46:47], v[46:47], off
	s_nop 0
	global_load_dwordx2 v[80:81], v[44:45], off
	ds_read_b128 v[90:93], v88
	ds_read_b128 v[94:97], v88 offset:16
	v_addc_co_u32_e64 v63, vcc, 0, v45, s[82:83]
	v_addc_co_u32_e64 v65, vcc, 0, v45, s[88:89]
	s_waitcnt lgkmcnt(1)
	v_mov_b32_e32 v110, v93
	v_addc_co_u32_e64 v67, vcc, 0, v45, s[84:85]
	v_addc_co_u32_e64 v69, vcc, 0, v45, s[86:87]
	v_addc_co_u32_e64 v49, vcc, 0, v45, s[74:75]
	v_addc_co_u32_e64 v51, vcc, 0, v45, s[80:81]
	v_addc_co_u32_e64 v53, vcc, 0, v45, s[76:77]
	v_addc_co_u32_e64 v55, vcc, 0, v45, s[78:79]
	v_addc_co_u32_e64 v23, vcc, 0, v45, s[66:67]
	v_addc_co_u32_e64 v25, vcc, 0, v45, s[0:1]
	v_addc_co_u32_e64 v35, vcc, 0, v45, s[68:69]
	v_addc_co_u32_e64 v37, vcc, 0, v45, s[70:71]
	v_addc_co_u32_e64 v5, vcc, 0, v45, s[58:59]
	v_addc_co_u32_e64 v7, vcc, 0, v45, s[64:65]
	v_addc_co_u32_e64 v19, vcc, 0, v45, s[60:61]
	v_addc_co_u32_e64 v21, vcc, 0, v45, s[62:63]
	v_addc_co_u32_e64 v27, vcc, 0, v45, s[50:51]
	v_addc_co_u32_e64 v31, vcc, 0, v45, s[54:55]
	v_addc_co_u32_e64 v29, vcc, 0, v45, s[52:53]
	v_addc_co_u32_e64 v33, vcc, 0, v45, s[56:57]
	v_addc_co_u32_e64 v3, vcc, 0, v45, s[38:39]
	v_addc_co_u32_e64 v9, vcc, 0, v45, s[48:49]
	v_addc_co_u32_e64 v11, vcc, 0, v45, s[40:41]
	v_addc_co_u32_e64 v13, vcc, 0, v45, s[42:43]
	v_addc_co_u32_e64 v15, vcc, 0, v45, s[44:45]
	v_addc_co_u32_e64 v17, vcc, 0, v45, s[46:47]
	s_mov_b64 s[0:1], 0xc0000
	v_lshl_add_u64 v[44:45], v[44:45], 0, s[0:1]
	global_load_dwordx2 v[62:63], v[62:63], off
	s_nop 0
	global_load_dwordx2 v[64:65], v[64:65], off
	s_nop 0
	global_load_dwordx2 v[66:67], v[66:67], off
	s_waitcnt vmcnt(0)
	v_pk_fma_f32 v[82:83], v[80:81], v[90:91], v[82:83] op_sel_hi:[1,0,1]
	s_nop 0
	v_pk_fma_f32 v[82:83], v[70:71], v[90:91], v[82:83] op_sel:[0,1,0]
	s_nop 0
	v_pk_fma_f32 v[82:83], v[72:73], v[92:93], v[82:83] op_sel_hi:[1,0,1]
	ds_read_b128 v[90:93], v88 offset:4096
	ds_read_b128 v[98:101], v88 offset:4112
	s_waitcnt lgkmcnt(1)
	v_pk_fma_f32 v[78:79], v[80:81], v[90:91], v[78:79] op_sel_hi:[1,0,1]
	s_nop 0
	v_pk_fma_f32 v[78:79], v[70:71], v[90:91], v[78:79] op_sel:[0,1,0]
	v_mov_b32_e32 v114, v93
	v_pk_fma_f32 v[112:113], v[72:73], v[92:93], v[78:79] op_sel_hi:[1,0,1]
	ds_read_b128 v[90:93], v88 offset:8192
	ds_read_b128 v[102:105], v88 offset:8208
	s_waitcnt lgkmcnt(1)
	v_pk_fma_f32 v[76:77], v[80:81], v[90:91], v[76:77] op_sel_hi:[1,0,1]
	s_nop 0
	v_pk_fma_f32 v[76:77], v[70:71], v[90:91], v[76:77] op_sel:[0,1,0]
	v_mov_b32_e32 v118, v93
	v_pk_fma_f32 v[116:117], v[72:73], v[92:93], v[76:77] op_sel_hi:[1,0,1]
	ds_read_b128 v[76:79], v88 offset:12288
	ds_read_b128 v[90:93], v88 offset:12304
	s_waitcnt lgkmcnt(1)
	v_pk_fma_f32 v[60:61], v[80:81], v[76:77], v[60:61] op_sel_hi:[1,0,1]
	s_nop 0
	v_pk_fma_f32 v[60:61], v[70:71], v[76:77], v[60:61] op_sel:[0,1,0]
	v_mov_b32_e32 v120, v79
	v_pk_fma_f32 v[60:61], v[72:73], v[78:79], v[60:61] op_sel_hi:[1,0,1]
	ds_read_b128 v[76:79], v88 offset:16384
	ds_read_b128 v[106:109], v88 offset:16400
	s_nop 0
	s_nop 0
	s_nop 0
	v_pk_fma_f32 v[60:61], v[74:75], v[120:121], v[60:61] op_sel_hi:[1,0,1]
	s_nop 0
	s_waitcnt lgkmcnt(1)
; __device__ __forceinline__ void phase_p0a(const Args& a, LAS unsigned char* lds) {
;     ...
;                 for (int kk = 0; kk < 32; ++kk) wv[kk] = *(const f32x2*)(wp + (size_t)(k0 + kk) * NMODC);
; #pragma unroll
;                 for (int kk = 0; kk < 32; ++kk) {
; #pragma unroll
;                     for (int bb = 0; bb < 5; ++bb) { const float sv = sil[bb * DM + wave * 128 + k0 + kk]; acc[bb][0] += sv * wv[kk][0]; acc[bb][1] += sv * wv[kk][1]; }
	v_pk_fma_f32 v[56:57], v[80:81], v[76:77], v[56:57] op_sel_hi:[1,0,1]
	v_pk_fma_f32 v[60:61], v[58:59], v[90:91], v[60:61] op_sel_hi:[1,0,1]
	v_pk_fma_f32 v[56:57], v[70:71], v[76:77], v[56:57] op_sel:[0,1,0]
	v_mov_b32_e32 v70, v79
	v_pk_fma_f32 v[56:57], v[72:73], v[78:79], v[56:57] op_sel_hi:[1,0,1]
	v_pk_fma_f32 v[72:73], v[74:75], v[110:111], v[82:83] op_sel_hi:[1,0,1]
	v_pk_fma_f32 v[76:77], v[74:75], v[114:115], v[112:113] op_sel_hi:[1,0,1]
	v_pk_fma_f32 v[78:79], v[74:75], v[118:119], v[116:117] op_sel_hi:[1,0,1]
	v_pk_fma_f32 v[70:71], v[74:75], v[70:71], v[56:57] op_sel_hi:[1,0,1]
	global_load_dwordx2 v[56:57], v[68:69], off
	v_pk_fma_f32 v[68:69], v[58:59], v[94:95], v[72:73] op_sel_hi:[1,0,1]
	v_pk_fma_f32 v[74:75], v[58:59], v[98:99], v[76:77] op_sel_hi:[1,0,1]
	v_pk_fma_f32 v[78:79], v[58:59], v[102:103], v[78:79] op_sel_hi:[1,0,1]
	s_waitcnt lgkmcnt(0)
	v_pk_fma_f32 v[58:59], v[58:59], v[106:107], v[70:71] op_sel_hi:[1,0,1]
	v_mov_b32_e32 v72, v97
	v_mov_b32_e32 v76, v101
	v_mov_b32_e32 v80, v105
	v_mov_b32_e32 v82, v93
	s_waitcnt vmcnt(3)
	v_pk_fma_f32 v[68:69], v[62:63], v[94:95], v[68:69] op_sel:[0,1,0]
	v_pk_fma_f32 v[74:75], v[62:63], v[98:99], v[74:75] op_sel:[0,1,0]
	v_pk_fma_f32 v[78:79], v[62:63], v[102:103], v[78:79] op_sel:[0,1,0]
	v_pk_fma_f32 v[60:61], v[62:63], v[90:91], v[60:61] op_sel:[0,1,0]
	v_pk_fma_f32 v[58:59], v[62:63], v[106:107], v[58:59] op_sel:[0,1,0]
	s_waitcnt vmcnt(2)
	v_pk_fma_f32 v[68:69], v[64:65], v[96:97], v[68:69] op_sel_hi:[1,0,1]
	v_pk_fma_f32 v[74:75], v[64:65], v[100:101], v[74:75] op_sel_hi:[1,0,1]
	v_pk_fma_f32 v[78:79], v[64:65], v[104:105], v[78:79] op_sel_hi:[1,0,1]
	v_pk_fma_f32 v[60:61], v[64:65], v[92:93], v[60:61] op_sel_hi:[1,0,1]
	v_pk_fma_f32 v[58:59], v[64:65], v[108:109], v[58:59] op_sel_hi:[1,0,1]
	v_mov_b32_e32 v64, v109
	s_waitcnt vmcnt(1)
	v_pk_fma_f32 v[68:69], v[66:67], v[72:73], v[68:69] op_sel_hi:[1,0,1]
	v_pk_fma_f32 v[70:71], v[66:67], v[76:77], v[74:75] op_sel_hi:[1,0,1]
	v_pk_fma_f32 v[62:63], v[66:67], v[80:81], v[78:79] op_sel_hi:[1,0,1]
	v_pk_fma_f32 v[60:61], v[66:67], v[82:83], v[60:61] op_sel_hi:[1,0,1]
	v_pk_fma_f32 v[58:59], v[66:67], v[64:65], v[58:59] op_sel_hi:[1,0,1]
	ds_read_b128 v[64:67], v88 offset:32
	global_load_dwordx2 v[76:77], v[48:49], off
	global_load_dwordx2 v[78:79], v[50:51], off
	global_load_dwordx2 v[80:81], v[52:53], off
	global_load_dwordx2 v[82:83], v[54:55], off
	ds_read_b128 v[48:51], v88 offset:48
	s_waitcnt vmcnt(4) lgkmcnt(1)
	v_pk_fma_f32 v[52:53], v[56:57], v[64:65], v[68:69] op_sel_hi:[1,0,1]
	v_mov_b32_e32 v92, v67
	s_waitcnt vmcnt(3)
	v_pk_fma_f32 v[52:53], v[76:77], v[64:65], v[52:53] op_sel:[0,1,0]
	s_waitcnt vmcnt(2)
	v_pk_fma_f32 v[90:91], v[78:79], v[66:67], v[52:53] op_sel_hi:[1,0,1]
	ds_read_b128 v[52:55], v88 offset:4128
	ds_read_b128 v[64:67], v88 offset:4144
	s_waitcnt lgkmcnt(1)
	v_pk_fma_f32 v[68:69], v[56:57], v[52:53], v[70:71] op_sel_hi:[1,0,1]
	s_nop 0
	v_pk_fma_f32 v[52:53], v[76:77], v[52:53], v[68:69] op_sel:[0,1,0]
	v_mov_b32_e32 v96, v55
	v_pk_fma_f32 v[94:95], v[78:79], v[54:55], v[52:53] op_sel_hi:[1,0,1]
	ds_read_b128 v[52:55], v88 offset:8224
	ds_read_b128 v[68:71], v88 offset:8240
	s_waitcnt lgkmcnt(1)
	v_pk_fma_f32 v[62:63], v[56:57], v[52:53], v[62:63] op_sel_hi:[1,0,1]
	s_nop 0
	v_pk_fma_f32 v[52:53], v[76:77], v[52:53], v[62:63] op_sel:[0,1,0]
	v_mov_b32_e32 v100, v55
	v_pk_fma_f32 v[98:99], v[78:79], v[54:55], v[52:53] op_sel_hi:[1,0,1]
	ds_read_b128 v[52:55], v88 offset:12320
	ds_read_b128 v[72:75], v88 offset:12336
	s_waitcnt lgkmcnt(1)
	v_pk_fma_f32 v[60:61], v[56:57], v[52:53], v[60:61] op_sel_hi:[1,0,1]
	s_nop 0
	v_pk_fma_f32 v[52:53], v[76:77], v[52:53], v[60:61] op_sel:[0,1,0]
	v_mov_b32_e32 v104, v55
	v_pk_fma_f32 v[102:103], v[78:79], v[54:55], v[52:53] op_sel_hi:[1,0,1]
	ds_read_b128 v[52:55], v88 offset:16416
	ds_read_b128 v[60:63], v88 offset:16432
	s_waitcnt lgkmcnt(1)
	v_pk_fma_f32 v[56:57], v[56:57], v[52:53], v[58:59] op_sel_hi:[1,0,1]
	s_nop 0
	v_pk_fma_f32 v[52:53], v[76:77], v[52:53], v[56:57] op_sel:[0,1,0]
	s_waitcnt vmcnt(1)
	v_pk_fma_f32 v[56:57], v[80:81], v[92:93], v[90:91] op_sel_hi:[1,0,1]
	v_pk_fma_f32 v[52:53], v[78:79], v[54:55], v[52:53] op_sel_hi:[1,0,1]
	v_mov_b32_e32 v54, v55
	v_pk_fma_f32 v[52:53], v[80:81], v[54:55], v[52:53] op_sel_hi:[1,0,1]
	global_load_dwordx2 v[54:55], v[22:23], off
	s_nop 0
	global_load_dwordx2 v[24:25], v[24:25], off
	v_pk_fma_f32 v[58:59], v[80:81], v[96:97], v[94:95] op_sel_hi:[1,0,1]
	v_pk_fma_f32 v[76:77], v[80:81], v[100:101], v[98:99] op_sel_hi:[1,0,1]
	v_pk_fma_f32 v[78:79], v[80:81], v[104:105], v[102:103] op_sel_hi:[1,0,1]
	global_load_dwordx2 v[80:81], v[34:35], off
	global_load_dwordx2 v[22:23], v[36:37], off
	s_waitcnt vmcnt(4)
	v_pk_fma_f32 v[34:35], v[82:83], v[48:49], v[56:57] op_sel_hi:[1,0,1]
	v_mov_b32_e32 v90, v51
	s_waitcnt vmcnt(3)
	v_pk_fma_f32 v[34:35], v[54:55], v[48:49], v[34:35] op_sel:[0,1,0]
	s_waitcnt vmcnt(2)
	v_pk_fma_f32 v[56:57], v[24:25], v[50:51], v[34:35] op_sel_hi:[1,0,1]
	v_pk_fma_f32 v[34:35], v[82:83], v[64:65], v[58:59] op_sel_hi:[1,0,1]
	s_waitcnt lgkmcnt(0)
	v_pk_fma_f32 v[48:49], v[82:83], v[60:61], v[52:53] op_sel_hi:[1,0,1]
	v_pk_fma_f32 v[34:35], v[54:55], v[64:65], v[34:35] op_sel:[0,1,0]
	v_mov_b32_e32 v64, v67
	v_pk_fma_f32 v[58:59], v[24:25], v[66:67], v[34:35] op_sel_hi:[1,0,1]
	v_pk_fma_f32 v[34:35], v[82:83], v[68:69], v[76:77] op_sel_hi:[1,0,1]
	v_pk_fma_f32 v[48:49], v[54:55], v[60:61], v[48:49] op_sel:[0,1,0]
	v_pk_fma_f32 v[34:35], v[54:55], v[68:69], v[34:35] op_sel:[0,1,0]
	v_mov_b32_e32 v68, v71
	v_pk_fma_f32 v[66:67], v[24:25], v[70:71], v[34:35] op_sel_hi:[1,0,1]
	v_pk_fma_f32 v[34:35], v[82:83], v[72:73], v[78:79] op_sel_hi:[1,0,1]
	v_mov_b32_e32 v70, v75
	v_pk_fma_f32 v[34:35], v[54:55], v[72:73], v[34:35] op_sel:[0,1,0]
	s_waitcnt vmcnt(1)
; __device__ __forceinline__ void phase_p0a(const Args& a, LAS unsigned char* lds) {
;     ...
;                 for (int kk = 0; kk < 32; ++kk) wv[kk] = *(const f32x2*)(wp + (size_t)(k0 + kk) * NMODC);
; #pragma unroll
;                 for (int kk = 0; kk < 32; ++kk) {
; #pragma unroll
;                     for (int bb = 0; bb < 5; ++bb) { const float sv = sil[bb * DM + wave * 128 + k0 + kk]; acc[bb][0] += sv * wv[kk][0]; acc[bb][1] += sv * wv[kk][1]; }
	v_pk_fma_f32 v[56:57], v[80:81], v[90:91], v[56:57] op_sel_hi:[1,0,1]
	v_pk_fma_f32 v[72:73], v[24:25], v[74:75], v[34:35] op_sel_hi:[1,0,1]
	v_pk_fma_f32 v[24:25], v[24:25], v[62:63], v[48:49] op_sel_hi:[1,0,1]
	v_mov_b32_e32 v74, v63
	ds_read_b128 v[34:37], v88 offset:64
	ds_read_b128 v[60:63], v88 offset:80
	ds_read_b128 v[48:51], v88 offset:4160
	ds_read_b128 v[52:55], v88 offset:8256
	v_pk_fma_f32 v[58:59], v[80:81], v[64:65], v[58:59] op_sel_hi:[1,0,1]
	v_pk_fma_f32 v[68:69], v[80:81], v[68:69], v[66:67] op_sel_hi:[1,0,1]
	v_pk_fma_f32 v[70:71], v[80:81], v[70:71], v[72:73] op_sel_hi:[1,0,1]
	v_pk_fma_f32 v[24:25], v[80:81], v[74:75], v[24:25] op_sel_hi:[1,0,1]
	ds_read_b128 v[64:67], v88 offset:4176
	global_load_dwordx2 v[74:75], v[4:5], off
	global_load_dwordx2 v[80:81], v[6:7], off
	global_load_dwordx2 v[82:83], v[18:19], off
	global_load_dwordx2 v[90:91], v[20:21], off
	s_waitcnt vmcnt(4) lgkmcnt(4)
	v_pk_fma_f32 v[4:5], v[22:23], v[34:35], v[56:57] op_sel_hi:[1,0,1]
	v_mov_b32_e32 v72, v37
	s_waitcnt vmcnt(3)
	v_pk_fma_f32 v[4:5], v[74:75], v[34:35], v[4:5] op_sel:[0,1,0]
	s_waitcnt vmcnt(2)
	v_pk_fma_f32 v[56:57], v[80:81], v[36:37], v[4:5] op_sel_hi:[1,0,1]
	s_waitcnt lgkmcnt(2)
	v_pk_fma_f32 v[4:5], v[22:23], v[48:49], v[58:59] op_sel_hi:[1,0,1]
	ds_read_b128 v[34:37], v88 offset:8272
	v_pk_fma_f32 v[4:5], v[74:75], v[48:49], v[4:5] op_sel:[0,1,0]
	s_waitcnt lgkmcnt(2)
	v_mov_b32_e32 v58, v55
	v_pk_fma_f32 v[48:49], v[80:81], v[50:51], v[4:5] op_sel_hi:[1,0,1]
	v_pk_fma_f32 v[4:5], v[22:23], v[52:53], v[68:69] op_sel_hi:[1,0,1]
	v_mov_b32_e32 v50, v51
	v_pk_fma_f32 v[4:5], v[74:75], v[52:53], v[4:5] op_sel:[0,1,0]
	s_waitcnt vmcnt(1)
	v_pk_fma_f32 v[72:73], v[82:83], v[72:73], v[56:57] op_sel_hi:[1,0,1]
	v_pk_fma_f32 v[52:53], v[80:81], v[54:55], v[4:5] op_sel_hi:[1,0,1]
	ds_read_b128 v[4:7], v88 offset:12352
	ds_read_b128 v[76:79], v88 offset:12368
	v_pk_fma_f32 v[92:93], v[82:83], v[58:59], v[52:53] op_sel_hi:[1,0,1]
	v_mov_b32_e32 v58, v63
	s_waitcnt lgkmcnt(1)
	v_pk_fma_f32 v[18:19], v[22:23], v[4:5], v[70:71] op_sel_hi:[1,0,1]
	s_nop 0
	v_pk_fma_f32 v[4:5], v[74:75], v[4:5], v[18:19] op_sel:[0,1,0]
	v_mov_b32_e32 v68, v7
	v_pk_fma_f32 v[54:55], v[80:81], v[6:7], v[4:5] op_sel_hi:[1,0,1]
	ds_read_b128 v[18:21], v88 offset:16448
	ds_read_b128 v[4:7], v88 offset:16464
	v_pk_fma_f32 v[68:69], v[82:83], v[68:69], v[54:55] op_sel_hi:[1,0,1]
	s_waitcnt lgkmcnt(1)
	v_pk_fma_f32 v[22:23], v[22:23], v[18:19], v[24:25] op_sel_hi:[1,0,1]
	s_nop 0
	v_pk_fma_f32 v[18:19], v[74:75], v[18:19], v[22:23] op_sel:[0,1,0]
	v_mov_b32_e32 v24, v21
	v_pk_fma_f32 v[22:23], v[80:81], v[20:21], v[18:19] op_sel_hi:[1,0,1]
	v_pk_fma_f32 v[80:81], v[82:83], v[50:51], v[48:49] op_sel_hi:[1,0,1]
	ds_read_b128 v[18:21], v88 offset:96
	v_pk_fma_f32 v[82:83], v[82:83], v[24:25], v[22:23] op_sel_hi:[1,0,1]
	ds_read_b128 v[22:25], v88 offset:4192
	global_load_dwordx2 v[94:95], v[26:27], off
	global_load_dwordx2 v[96:97], v[30:31], off
	global_load_dwordx2 v[56:57], v[28:29], off
	global_load_dwordx2 v[70:71], v[32:33], off
	s_waitcnt vmcnt(4)
	v_pk_fma_f32 v[26:27], v[90:91], v[60:61], v[72:73] op_sel_hi:[1,0,1]
	s_waitcnt vmcnt(3)
	v_pk_fma_f32 v[26:27], v[94:95], v[60:61], v[26:27] op_sel:[0,1,0]
	s_waitcnt vmcnt(2)
	v_pk_fma_f32 v[60:61], v[96:97], v[62:63], v[26:27] op_sel_hi:[1,0,1]
	ds_read_b128 v[26:29], v88 offset:8288
	global_load_dwordx2 v[74:75], v[2:3], off
	global_load_dwordx2 v[72:73], v[8:9], off
	global_load_dwordx2 v[54:55], v[10:11], off
	global_load_dwordx2 v[52:53], v[12:13], off
	global_load_dwordx2 v[50:51], v[14:15], off
	global_load_dwordx2 v[48:49], v[16:17], off
	v_pk_fma_f32 v[2:3], v[90:91], v[64:65], v[80:81] op_sel_hi:[1,0,1]
	v_mov_b32_e32 v12, v67
	v_pk_fma_f32 v[2:3], v[94:95], v[64:65], v[2:3] op_sel:[0,1,0]
	ds_read_b128 v[30:33], v88 offset:12384
	v_pk_fma_f32 v[10:11], v[96:97], v[66:67], v[2:3] op_sel_hi:[1,0,1]
	v_pk_fma_f32 v[2:3], v[90:91], v[34:35], v[92:93] op_sel_hi:[1,0,1]
	v_mov_b32_e32 v14, v37
	v_pk_fma_f32 v[2:3], v[94:95], v[34:35], v[2:3] op_sel:[0,1,0]
	s_waitcnt vmcnt(7)
	v_pk_fma_f32 v[58:59], v[56:57], v[58:59], v[60:61] op_sel_hi:[1,0,1]
	v_pk_fma_f32 v[16:17], v[96:97], v[36:37], v[2:3] op_sel_hi:[1,0,1]
	v_pk_fma_f32 v[2:3], v[90:91], v[76:77], v[68:69] op_sel_hi:[1,0,1]
	ds_read_b128 v[34:37], v88 offset:16480
	v_pk_fma_f32 v[60:61], v[56:57], v[12:13], v[10:11] op_sel_hi:[1,0,1]
	s_waitcnt lgkmcnt(5)
	v_pk_fma_f32 v[8:9], v[90:91], v[4:5], v[82:83] op_sel_hi:[1,0,1]
	v_pk_fma_f32 v[2:3], v[94:95], v[76:77], v[2:3] op_sel:[0,1,0]
	s_waitcnt vmcnt(6) lgkmcnt(3)
; __device__ __forceinline__ void phase_p0a(const Args& a, LAS unsigned char* lds) {
;     ...
;                 for (int kk = 0; kk < 32; ++kk) wv[kk] = *(const f32x2*)(wp + (size_t)(k0 + kk) * NMODC);
; #pragma unroll
;                 for (int kk = 0; kk < 32; ++kk) {
; #pragma unroll
;                     for (int bb = 0; bb < 5; ++bb) { const float sv = sil[bb * DM + wave * 128 + k0 + kk]; acc[bb][0] += sv * wv[kk][0]; acc[bb][1] += sv * wv[kk][1]; }
;                 }
;             }
; #pragma unroll
;             for (int bb = 0; bb < 5; ++bb) { part[(wave * 5 + bb) * 128 + 2 * lane] = acc[bb][0]; part[(wave * 5 + bb) * 128 + 2 * lane + 1] = acc[bb][1]; }
;             __syncthreads();
;             for (int idx = tid; idx < 640; idx += NTHREADS) { const int bb = idx >> 7, cn = idx & 127; float s = b_mod[l * NMODC + nb * 128 + cn];
; #pragma unroll
;                 for (int w = 0; w < 8; ++w) s += part[(w * 5 + bb) * 128 + cn];
;                 mod[((size_t)l * 5 + bb) * NMODC + nb * 128 + cn] = s; }
	v_pk_fma_f32 v[60:61], v[70:71], v[22:23], v[60:61] op_sel_hi:[1,0,1]
	v_mov_b32_e32 v62, v79
	v_pk_fma_f32 v[64:65], v[96:97], v[78:79], v[2:3] op_sel_hi:[1,0,1]
	v_pk_fma_f32 v[2:3], v[94:95], v[4:5], v[8:9] op_sel:[0,1,0]
	v_pk_fma_f32 v[76:77], v[56:57], v[14:15], v[16:17] op_sel_hi:[1,0,1]
	v_pk_fma_f32 v[58:59], v[70:71], v[18:19], v[58:59] op_sel_hi:[1,0,1]
	v_pk_fma_f32 v[66:67], v[96:97], v[6:7], v[2:3] op_sel_hi:[1,0,1]
	v_mov_b32_e32 v68, v7
	v_pk_fma_f32 v[78:79], v[56:57], v[62:63], v[64:65] op_sel_hi:[1,0,1]
	v_mov_b32_e32 v62, v25
	ds_read_b128 v[2:5], v88 offset:112
	ds_read_b128 v[6:9], v88 offset:4208
	ds_read_b128 v[10:13], v88 offset:8304
	v_pk_fma_f32 v[80:81], v[56:57], v[68:69], v[66:67] op_sel_hi:[1,0,1]
	ds_read_b128 v[14:17], v88 offset:12400
	v_mov_b32_e32 v56, v21
	s_waitcnt lgkmcnt(6)
	v_mov_b32_e32 v66, v29
	s_waitcnt vmcnt(5)
	v_pk_fma_f32 v[22:23], v[74:75], v[22:23], v[60:61] op_sel:[0,1,0]
	v_pk_fma_f32 v[18:19], v[74:75], v[18:19], v[58:59] op_sel:[0,1,0]
	s_waitcnt vmcnt(4)
	v_pk_fma_f32 v[60:61], v[72:73], v[24:25], v[22:23] op_sel_hi:[1,0,1]
	v_pk_fma_f32 v[24:25], v[70:71], v[26:27], v[76:77] op_sel_hi:[1,0,1]
	v_pk_fma_f32 v[58:59], v[72:73], v[20:21], v[18:19] op_sel_hi:[1,0,1]
	ds_read_b128 v[18:21], v88 offset:16496
	v_pk_fma_f32 v[24:25], v[74:75], v[26:27], v[24:25] op_sel:[0,1,0]
	s_waitcnt lgkmcnt(6)
	v_pk_fma_f32 v[26:27], v[70:71], v[30:31], v[78:79] op_sel_hi:[1,0,1]
	v_pk_fma_f32 v[64:65], v[72:73], v[28:29], v[24:25] op_sel_hi:[1,0,1]
	v_pk_fma_f32 v[26:27], v[74:75], v[30:31], v[26:27] op_sel:[0,1,0]
	s_waitcnt lgkmcnt(5)
	v_pk_fma_f32 v[30:31], v[70:71], v[34:35], v[80:81] op_sel_hi:[1,0,1]
	v_pk_fma_f32 v[68:69], v[72:73], v[32:33], v[26:27] op_sel_hi:[1,0,1]
	v_pk_fma_f32 v[30:31], v[74:75], v[34:35], v[30:31] op_sel:[0,1,0]
	v_mov_b32_e32 v32, v33
	v_mov_b32_e32 v34, v37
	v_pk_fma_f32 v[36:37], v[72:73], v[36:37], v[30:31] op_sel_hi:[1,0,1]
	s_waitcnt vmcnt(3)
	v_pk_fma_f32 v[56:57], v[54:55], v[56:57], v[58:59] op_sel_hi:[1,0,1]
	v_pk_fma_f32 v[58:59], v[54:55], v[62:63], v[60:61] op_sel_hi:[1,0,1]
	v_pk_fma_f32 v[60:61], v[54:55], v[66:67], v[64:65] op_sel_hi:[1,0,1]
	v_pk_fma_f32 v[32:33], v[54:55], v[32:33], v[68:69] op_sel_hi:[1,0,1]
	v_pk_fma_f32 v[34:35], v[54:55], v[34:35], v[36:37] op_sel_hi:[1,0,1]
	s_waitcnt vmcnt(2) lgkmcnt(4)
	v_pk_fma_f32 v[36:37], v[52:53], v[2:3], v[56:57] op_sel_hi:[1,0,1]
	s_waitcnt lgkmcnt(3)
	v_pk_fma_f32 v[54:55], v[52:53], v[6:7], v[58:59] op_sel_hi:[1,0,1]
	s_waitcnt lgkmcnt(2)
	v_pk_fma_f32 v[56:57], v[52:53], v[10:11], v[60:61] op_sel_hi:[1,0,1]
	s_waitcnt lgkmcnt(1)
	v_pk_fma_f32 v[32:33], v[52:53], v[14:15], v[32:33] op_sel_hi:[1,0,1]
	s_waitcnt lgkmcnt(0)
	v_pk_fma_f32 v[34:35], v[52:53], v[18:19], v[34:35] op_sel_hi:[1,0,1]
	s_waitcnt vmcnt(1)
	v_pk_fma_f32 v[2:3], v[50:51], v[2:3], v[36:37] op_sel:[0,1,0]
	v_pk_fma_f32 v[6:7], v[50:51], v[6:7], v[54:55] op_sel:[0,1,0]
	v_pk_fma_f32 v[10:11], v[50:51], v[10:11], v[56:57] op_sel:[0,1,0]
	v_pk_fma_f32 v[14:15], v[50:51], v[14:15], v[32:33] op_sel:[0,1,0]
	v_pk_fma_f32 v[18:19], v[50:51], v[18:19], v[34:35] op_sel:[0,1,0]
	v_mov_b32_e32 v22, v5
	v_mov_b32_e32 v24, v9
	v_mov_b32_e32 v26, v13
	v_mov_b32_e32 v28, v17
	v_mov_b32_e32 v30, v21
	s_waitcnt vmcnt(0)
	v_pk_fma_f32 v[2:3], v[48:49], v[4:5], v[2:3] op_sel_hi:[1,0,1]
	v_pk_fma_f32 v[4:5], v[48:49], v[8:9], v[6:7] op_sel_hi:[1,0,1]
	v_pk_fma_f32 v[6:7], v[48:49], v[12:13], v[10:11] op_sel_hi:[1,0,1]
	v_pk_fma_f32 v[8:9], v[48:49], v[16:17], v[14:15] op_sel_hi:[1,0,1]
	v_pk_fma_f32 v[10:11], v[48:49], v[20:21], v[18:19] op_sel_hi:[1,0,1]
	v_add_u32_e32 v88, 0x80, v88
	v_pk_fma_f32 v[82:83], v[46:47], v[22:23], v[2:3] op_sel_hi:[1,0,1]
	v_pk_fma_f32 v[78:79], v[46:47], v[24:25], v[4:5] op_sel_hi:[1,0,1]
	v_pk_fma_f32 v[76:77], v[46:47], v[26:27], v[6:7] op_sel_hi:[1,0,1]
	v_pk_fma_f32 v[60:61], v[46:47], v[28:29], v[8:9] op_sel_hi:[1,0,1]
	v_pk_fma_f32 v[56:57], v[46:47], v[30:31], v[10:11] op_sel_hi:[1,0,1]
	s_cbranch_scc0 .LBB0_913
	ds_write2st64_b64 v87, v[82:83], v[78:79] offset0:40 offset1:41
	ds_write2st64_b64 v87, v[76:77], v[60:61] offset0:42 offset1:43
	ds_write_b64 v87, v[56:57] offset:22528
	s_waitcnt lgkmcnt(0)
	s_barrier
	s_and_saveexec_b64 s[0:1], s[36:37]
	s_cbranch_execz .LBB0_911
	s_mul_i32 s5, s72, 0x1800
	s_add_i32 s34, s5, s4
	v_or_b32_e32 v2, s34, v85
	v_readlane_b32 s40, v254, 62
	s_ashr_i32 s5, s4, 31
	v_ashrrev_i32_e32 v3, 31, v2
	v_readlane_b32 s50, v255, 8
	v_readlane_b32 s51, v255, 9
	s_mul_hi_i32 s39, s72, 5
	s_mul_i32 s38, s72, 5
	v_lshl_add_u64 v[2:3], v[2:3], 2, s[50:51]
	v_lshl_add_u64 v[4:5], s[4:5], 2, v[42:43]
	s_mov_b64 s[4:5], 0
	v_mov_b32_e32 v6, v38
	v_readlane_b32 s41, v254, 63
	v_readlane_b32 s42, v255, 0
	v_readlane_b32 s43, v255, 1
	v_readlane_b32 s44, v255, 2
	v_readlane_b32 s45, v255, 3
	v_readlane_b32 s46, v255, 4
	v_readlane_b32 s47, v255, 5
	v_readlane_b32 s48, v255, 6
	v_readlane_b32 s49, v255, 7
	v_readlane_b32 s52, v255, 10
	v_readlane_b32 s53, v255, 11
	v_readlane_b32 s54, v255, 12
	v_readlane_b32 s55, v255, 13
